# v14 + XCD leaders no longer add to the per-XCD XGEN word nor wait for that atomic (nobody polls XGEN after the flattened release)
# baseline (speedup 1.0000x reference)
.LBB0_91:
	s_or_b64 exec, exec, s[6:7]
	s_mov_b64 s[6:7], exec
	v_mbcnt_lo_u32_b32 v1, s6, 0
	v_mbcnt_hi_u32_b32 v1, s7, v1
	v_cmp_eq_u32_e32 vcc, 0, v1
	s_waitcnt vmcnt(0)
	buffer_inv sc1
	s_and_saveexec_b64 s[8:9], vcc
	s_cbranch_execz .LBB0_93
	s_bcnt1_i32_b64 s6, s[6:7]
	v_mov_b32_e32 v1, 0x2000
	v_mov_b32_e32 v2, s6
.LBB0_93:
	s_or_b64 exec, exec, s[8:9]
	s_waitcnt vmcnt(0)

.LBB0_175:
	s_or_b64 exec, exec, s[6:7]
	s_mov_b64 s[6:7], exec
	v_mbcnt_lo_u32_b32 v1, s6, 0
	v_mbcnt_hi_u32_b32 v1, s7, v1
	v_cmp_eq_u32_e32 vcc, 0, v1
	s_waitcnt vmcnt(0)
	buffer_inv sc1
	s_and_saveexec_b64 s[8:9], vcc
	s_cbranch_execz .LBB0_177
	s_bcnt1_i32_b64 s6, s[6:7]
	v_mov_b32_e32 v1, 0x2000
	v_mov_b32_e32 v2, s6
.LBB0_177:
	s_or_b64 exec, exec, s[8:9]
	s_waitcnt vmcnt(0)

.LBB0_361:
	s_or_b64 exec, exec, s[6:7]
	s_mov_b64 s[6:7], exec
	v_mbcnt_lo_u32_b32 v1, s6, 0
	v_mbcnt_hi_u32_b32 v1, s7, v1
	v_cmp_eq_u32_e32 vcc, 0, v1
	s_waitcnt vmcnt(0)
	buffer_inv sc1
	s_and_saveexec_b64 s[8:9], vcc
	s_cbranch_execz .LBB0_363
	s_bcnt1_i32_b64 s6, s[6:7]
	v_mov_b32_e32 v1, 0x2000
	v_mov_b32_e32 v2, s6
.LBB0_363:
	s_or_b64 exec, exec, s[8:9]
	s_waitcnt vmcnt(0)

.LBB0_522:
	s_or_b64 exec, exec, s[10:11]
	s_mov_b64 s[10:11], exec
	v_mbcnt_lo_u32_b32 v1, s10, 0
	v_mbcnt_hi_u32_b32 v1, s11, v1
	v_cmp_eq_u32_e32 vcc, 0, v1
	s_waitcnt vmcnt(0)
	buffer_inv sc1
	s_and_saveexec_b64 s[12:13], vcc
	s_cbranch_execz .LBB0_524
	s_bcnt1_i32_b64 s10, s[10:11]
	v_mov_b32_e32 v1, 0x2000
	v_mov_b32_e32 v2, s10
.LBB0_524:
	s_or_b64 exec, exec, s[12:13]
	s_waitcnt vmcnt(0)

.LBB0_672:
	s_or_b64 exec, exec, s[6:7]
	s_mov_b64 s[6:7], exec
	v_mbcnt_lo_u32_b32 v1, s6, 0
	v_mbcnt_hi_u32_b32 v1, s7, v1
	v_cmp_eq_u32_e32 vcc, 0, v1
	s_waitcnt vmcnt(0)
	buffer_inv sc1
	s_and_saveexec_b64 s[10:11], vcc
	s_cbranch_execz .LBB0_674
	s_bcnt1_i32_b64 s6, s[6:7]
	v_mov_b32_e32 v1, 0x2000
	v_mov_b32_e32 v2, s6
.LBB0_674:
	s_or_b64 exec, exec, s[10:11]
	s_waitcnt vmcnt(0)

.LBB0_926:
	s_or_b64 exec, exec, s[6:7]
	s_mov_b64 s[6:7], exec
	v_mbcnt_lo_u32_b32 v2, s6, 0
	v_mbcnt_hi_u32_b32 v2, s7, v2
	v_cmp_eq_u32_e32 vcc, 0, v2
	s_waitcnt vmcnt(0)
	buffer_inv sc1
	s_and_saveexec_b64 s[10:11], vcc
	s_cbranch_execz .LBB0_928
	s_bcnt1_i32_b64 s6, s[6:7]
	v_mov_b32_e32 v2, 0x2000
	v_mov_b32_e32 v3, s6
.LBB0_928:
	s_or_b64 exec, exec, s[10:11]
	s_waitcnt vmcnt(0)

.LBB0_983:
	s_or_b64 exec, exec, s[4:5]
	s_mov_b64 s[4:5], exec
	v_mbcnt_lo_u32_b32 v2, s4, 0
	v_mbcnt_hi_u32_b32 v2, s5, v2
	v_cmp_eq_u32_e32 vcc, 0, v2
	s_waitcnt vmcnt(0)
	buffer_inv sc1
	s_and_saveexec_b64 s[6:7], vcc
	s_cbranch_execz .LBB0_985
	s_bcnt1_i32_b64 s4, s[4:5]
	v_mov_b32_e32 v2, 0x2000
	v_mov_b32_e32 v3, s4
.LBB0_985:
	s_or_b64 exec, exec, s[6:7]
	s_waitcnt vmcnt(0)

.LBB0_1068:
	s_or_b64 exec, exec, s[8:9]
	s_mov_b64 s[8:9], exec
	v_mbcnt_lo_u32_b32 v2, s8, 0
	v_mbcnt_hi_u32_b32 v2, s9, v2
	v_cmp_eq_u32_e32 vcc, 0, v2
	s_waitcnt vmcnt(0)
	buffer_inv sc1
	s_and_saveexec_b64 s[10:11], vcc
	s_cbranch_execz .LBB0_1070
	s_bcnt1_i32_b64 s8, s[8:9]
	v_mov_b32_e32 v2, 0x2000
	v_mov_b32_e32 v3, s8
.LBB0_1070:
	s_or_b64 exec, exec, s[10:11]
	s_waitcnt vmcnt(0)

.LBB0_1197:
	s_or_b64 exec, exec, s[6:7]
	s_mov_b64 s[6:7], exec
	v_mbcnt_lo_u32_b32 v2, s6, 0
	v_mbcnt_hi_u32_b32 v2, s7, v2
	v_cmp_eq_u32_e32 vcc, 0, v2
	s_waitcnt vmcnt(0)
	buffer_inv sc1
	s_and_saveexec_b64 s[16:17], vcc
	s_cbranch_execz .LBB0_1199
	s_bcnt1_i32_b64 s6, s[6:7]
	v_mov_b32_e32 v2, 0x2000
	v_mov_b32_e32 v3, s6
.LBB0_1199:
	s_or_b64 exec, exec, s[16:17]
	s_waitcnt vmcnt(0)

.LBB0_1272:
	s_or_b64 exec, exec, s[16:17]
	s_mov_b64 s[16:17], exec
	v_mbcnt_lo_u32_b32 v2, s16, 0
	v_mbcnt_hi_u32_b32 v2, s17, v2
	v_cmp_eq_u32_e32 vcc, 0, v2
	s_waitcnt vmcnt(0)
	buffer_inv sc1
	s_and_saveexec_b64 s[18:19], vcc
	s_cbranch_execz .LBB0_1274
	s_bcnt1_i32_b64 s16, s[16:17]
	v_mov_b32_e32 v2, 0x2000
	v_mov_b32_e32 v3, s16
.LBB0_1274:
	s_or_b64 exec, exec, s[18:19]
	s_waitcnt vmcnt(0)

.LBB0_1365:
	s_or_b64 exec, exec, s[14:15]
	s_mov_b64 s[14:15], exec
	v_mbcnt_lo_u32_b32 v2, s14, 0
	v_mbcnt_hi_u32_b32 v2, s15, v2
	v_cmp_eq_u32_e32 vcc, 0, v2
	s_waitcnt vmcnt(0)
	buffer_inv sc1
	s_and_saveexec_b64 s[16:17], vcc
	s_cbranch_execz .LBB0_1367
	s_bcnt1_i32_b64 s14, s[14:15]
	v_mov_b32_e32 v2, 0x2000
	v_mov_b32_e32 v3, s14
.LBB0_1367:
	s_or_b64 exec, exec, s[16:17]
	s_waitcnt vmcnt(0)

.LBB0_1444:
	s_or_b64 exec, exec, s[6:7]
	s_mov_b64 s[6:7], exec
	v_mbcnt_lo_u32_b32 v2, s6, 0
	v_mbcnt_hi_u32_b32 v2, s7, v2
	v_cmp_eq_u32_e32 vcc, 0, v2
	s_waitcnt vmcnt(0)
	buffer_inv sc1
	s_and_saveexec_b64 s[8:9], vcc
	s_cbranch_execz .LBB0_1446
	s_bcnt1_i32_b64 s6, s[6:7]
	v_mov_b32_e32 v2, 0x2000
	v_mov_b32_e32 v3, s6
.LBB0_1446:
	s_or_b64 exec, exec, s[8:9]
	s_waitcnt vmcnt(0)
